# bar_nowb + na_waits + P1 rotation 12
# baseline (speedup 1.0000x reference)
.LBB0_103:
	s_cmp_lt_i32 s82, 2
	s_cselect_b64 s[4:5], -1, 0
	s_add_u32 s6, s80, 0x1100000
	v_writelane_b32 v255, s84, 25
	s_addc_u32 s7, s81, 0
	v_writelane_b32 v255, s6, 26
	s_nop 1
	v_writelane_b32 v255, s7, 27
	s_add_u32 s6, s80, 0x1300000
	s_addc_u32 s7, s81, 0
	v_writelane_b32 v255, s6, 28
	s_nop 1
	v_writelane_b32 v255, s7, 29
	s_add_u32 s6, s80, 0x1b00000
	s_addc_u32 s7, s81, 0
	s_add_u32 s69, s80, 0x2600000
	v_writelane_b32 v255, s6, 30
	s_addc_u32 s70, s81, 0
	s_nop 0
	v_writelane_b32 v255, s7, 31
	s_add_u32 s6, s80, 0x2c00000
	s_addc_u32 s7, s81, 0
	s_add_u32 s60, s80, 0x8c00000
	s_addc_u32 s61, s81, 0
	s_add_u32 s96, s80, 0xdc00000
	s_addc_u32 s91, s81, 0
	s_add_u32 s62, s80, 0x7c00000
	v_writelane_b32 v255, s6, 32
	s_addc_u32 s63, s81, 0
	s_and_b64 s[28:29], s[4:5], s[0:1]
	v_writelane_b32 v255, s7, 33
	s_andn2_b64 vcc, exec, s[28:29]
	s_cbranch_vccnz .LBB0_220
	s_cmpk_lt_i32 s2, 0x590
	s_cselect_b64 s[4:5], -1, 0
	s_cmpk_gt_i32 s2, 0x58f
	v_readfirstlane_b32 s6, v216
	s_cbranch_scc1 .LBB0_107
	s_cmpk_gt_i32 s2, 0x57f
	s_cbranch_scc1 .LBB0_108
	s_ashr_i32 s0, s2, 31
	s_lshr_b32 s0, s0, 29
	s_add_i32 s0, s2, s0
	s_ashr_i32 s1, s0, 3
	s_and_b32 s0, s0, -8
	s_sub_i32 s0, s2, s0
	s_cmp_lt_i32 s0, 0
	s_movk_i32 s7, 0xb1
	s_cselect_b32 s7, s7, 0xb0
	s_mul_i32 s0, s0, s7
	s_add_i32 s0, s0, s1
	s_mul_hi_i32 s1, s0, 0x2e8ba2e9
	s_lshr_b32 s7, s1, 31
	s_ashr_i32 s1, s1, 5
	s_add_i32 s1, s1, s7
	s_lshl_b32 s7, s1, 3
	s_mulk_i32 s1, 0xb0
	s_sub_i32 s0, s0, s1
	s_sext_i32_i16 s1, s0
	s_bfe_u32 s1, s1, 0x3001c
	s_add_i32 s1, s0, s1
	s_bfe_u32 s8, s1, 0xd0003
	s_and_b32 s1, s1, 0xfff8
	s_sub_i32 s0, s0, s1
	s_sext_i32_i16 s0, s0
	s_add_i32 s8, s8, 12
	s_add_i32 s38, s7, s0
	s_bfe_i32 s0, s8, 0x80000
	s_mul_i32 s0, s0, 0xffbb
	s_bfe_u32 s0, s0, 0x80008
	s_add_i32 s0, s0, s8
	s_bfe_i32 s1, s0, 0x80000
	s_and_b32 s1, 0xffff, s1
	s_lshr_b32 s1, s1, 4
	s_bfe_u32 s0, s0, 0x10007
	s_add_i32 s0, s1, s0
	s_mul_i32 s0, s0, 22
	s_sub_i32 s0, s8, s0
	s_mov_b32 s59, 0
	s_sext_i32_i8 s90, s0
	s_mov_b64 s[0:1], -1
	s_andn2_b64 vcc, exec, s[4:5]
	v_lshlrev_b32_e32 v16, 2, v216
	s_cbranch_vccz .LBB0_109
	s_branch .LBB0_178

.LBB0_117:
	s_andn2_b64 vcc, exec, s[12:13]
	s_mov_b32 s69, 1
	s_cbranch_vccnz .LBB0_119
	s_ashr_i32 s5, s4, 31
	s_lshr_b32 s5, s5, 29
	s_add_i32 s5, s4, s5
	s_ashr_i32 s12, s5, 3
	s_and_b32 s5, s5, -8
	s_sub_i32 s4, s4, s5
	s_cmp_lt_i32 s4, 0
	s_movk_i32 s5, 0xb1
	s_cselect_b32 s5, s5, 0xb0
	s_mul_i32 s4, s4, s5
	s_add_i32 s4, s4, s12
	s_mul_hi_i32 s5, s4, 0x2e8ba2e9
	s_lshr_b32 s12, s5, 31
	s_ashr_i32 s5, s5, 5
	s_add_i32 s5, s5, s12
	s_lshl_b32 s12, s5, 3
	s_sub_i32 s13, 64, s12
	s_min_i32 s13, s13, 8
	s_abs_i32 s14, s13
	v_cvt_f32_u32_e32 v0, s14
	s_sub_i32 s16, 0, s14
	s_mulk_i32 s5, 0xb0
	s_sub_i32 s4, s4, s5
	v_rcp_iflag_f32_e32 v0, v0
	s_abs_i32 s5, s4
	s_xor_b32 s15, s4, s13
	s_ashr_i32 s15, s15, 31
	v_mul_f32_e32 v0, 0x4f7ffffe, v0
	v_cvt_u32_f32_e32 v0, v0
	s_mov_b32 s69, 0
	v_readfirstlane_b32 s17, v0
	s_mul_i32 s16, s16, s17
	s_mul_hi_u32 s16, s17, s16
	s_add_i32 s17, s17, s16
	s_mul_hi_u32 s16, s5, s17
	s_mul_i32 s17, s16, s14
	s_sub_i32 s5, s5, s17
	s_add_i32 s17, s16, 1
	s_sub_i32 s18, s5, s14
	s_cmp_ge_u32 s5, s14
	s_cselect_b32 s16, s17, s16
	s_cselect_b32 s5, s18, s5
	s_add_i32 s17, s16, 1
	s_cmp_ge_u32 s5, s14
	s_cselect_b32 s5, s17, s16
	s_xor_b32 s5, s5, s15
	s_sub_i32 s5, s5, s15
	s_mul_i32 s13, s5, s13
	s_sub_i32 s4, s4, s13
	s_add_i32 s5, s5, 12
	s_add_i32 s42, s12, s4
	s_sext_i32_i16 s4, s5
	s_mulk_i32 s4, 0xba3
	s_lshr_b32 s12, s4, 31
	s_lshr_b32 s4, s4, 16
	s_add_i32 s4, s4, s12
	s_mul_i32 s4, s4, 22
	s_sub_i32 s4, s5, s4
	s_sext_i32_i16 s44, s4
